# hg_finish: software-pipelined loop, same scheme as rw_finish
# speedup vs baseline: 1.0142x; 1.0022x over previous
.LBB0_169:
	s_ashr_i32 s4, s14, 2
	s_mov_b32 s6, 0x358637bd
	v_mov_b64_e32 v[6:7], s[6:7]
	s_ashr_i32 s5, s4, 31
	s_mul_i32 s6, s4, 0xc00
	s_mul_hi_i32 s7, s4, 0xc00
	s_add_u32 s6, s12, s6
	s_addc_u32 s7, s13, s7
	s_lshl_b64 s[4:5], s[4:5], 10
	v_lshl_add_u64 v[10:11], v[2:3], 2, s[6:7]
	v_lshl_add_u64 v[26:27], v[4:5], 0, s[4:5]
	v_lshl_add_u64 v[8:9], v[10:11], 0, s[20:21]
	global_load_dword v0, v[26:27], off
	global_load_dword v31, v[26:27], off offset:256
	v_add_co_u32_e32 v10, vcc, s81, v10
	global_load_dword v33, v[26:27], off offset:512
	global_load_dword v35, v[8:9], off offset:256
	global_load_dword v37, v[8:9], off offset:512
	v_addc_co_u32_e32 v11, vcc, 0, v11, vcc
	global_load_dword v39, v[26:27], off offset:768
	global_load_dword v41, v[8:9], off offset:768
	global_load_dword v47, v[10:11], off offset:1024
	s_add_i32 s14, s14, s41
	s_cmp_gt_i32 s14, 0xffff
	s_cselect_b32 s98, 0, 1
	global_load_dword v128, v[8:9], off offset:256
	global_load_dword v128, v[8:9], off offset:256
	global_load_dword v128, v[8:9], off offset:256
	global_load_dword v128, v[8:9], off offset:256
.Lhgf_loop:
	s_cmp_eq_u32 s98, 0
	s_cbranch_scc1 .Lhgf_tail1
	s_ashr_i32 s4, s14, 2
	s_mov_b32 s6, 0x358637bd
	v_mov_b64_e32 v[70:71], s[6:7]
	s_ashr_i32 s5, s4, 31
	s_mul_i32 s6, s4, 0xc00
	s_mul_hi_i32 s7, s4, 0xc00
	s_add_u32 s6, s12, s6
	s_addc_u32 s7, s13, s7
	s_lshl_b64 s[4:5], s[4:5], 10
	v_lshl_add_u64 v[74:75], v[2:3], 2, s[6:7]
	v_lshl_add_u64 v[90:91], v[4:5], 0, s[4:5]
	v_lshl_add_u64 v[72:73], v[74:75], 0, s[20:21]
	global_load_dword v64, v[90:91], off
	global_load_dword v95, v[90:91], off offset:256
	v_add_co_u32_e32 v74, vcc, s81, v74
	global_load_dword v97, v[90:91], off offset:512
	global_load_dword v99, v[72:73], off offset:256
	global_load_dword v101, v[72:73], off offset:512
	v_addc_co_u32_e32 v75, vcc, 0, v75, vcc
	global_load_dword v103, v[90:91], off offset:768
	global_load_dword v105, v[72:73], off offset:768
	global_load_dword v111, v[74:75], off offset:1024
	s_add_i32 s14, s14, s41
	s_cmp_gt_i32 s14, 0xffff
	s_cselect_b32 s98, 0, 1
	v_mov_b32_e32 v21, v1
	v_mov_b32_e32 v20, v1
	v_mov_b32_e32 v19, v1
	v_mov_b32_e32 v18, v1
	v_mov_b32_e32 v23, v1
	v_mov_b32_e32 v22, v1
	v_mov_b32_e32 v17, v1
	v_mov_b32_e32 v16, v1
	v_mov_b32_e32 v25, v1
	v_mov_b32_e32 v24, v1
	v_mov_b32_e32 v15, v1
	v_mov_b32_e32 v14, v1
	v_mov_b32_e32 v27, v1
	v_mov_b32_e32 v26, v1
	v_mov_b32_e32 v13, v1
	v_mov_b32_e32 v12, v1
	s_waitcnt vmcnt(19)
	v_lshlrev_b32_e32 v28, 16, v0
	v_and_b32_e32 v29, 0xffff0000, v0
	s_waitcnt vmcnt(17)
	v_lshlrev_b32_e32 v32, 16, v33
	s_waitcnt vmcnt(16)
	v_lshlrev_b32_e32 v34, 16, v35
	s_waitcnt vmcnt(15)
	v_lshlrev_b32_e32 v36, 16, v37
	v_and_b32_e32 v37, 0xffff0000, v37
	s_waitcnt vmcnt(13)
	v_lshlrev_b32_e32 v40, 16, v41
	v_and_b32_e32 v41, 0xffff0000, v41
	v_and_b32_e32 v35, 0xffff0000, v35
	v_pk_mul_f32 v[44:45], v[36:37], v[36:37]
	s_waitcnt vmcnt(12)
	v_lshlrev_b32_e32 v46, 16, v47
	v_and_b32_e32 v47, 0xffff0000, v47
	v_pk_mul_f32 v[48:49], v[40:41], v[40:41]
	v_pk_mul_f32 v[42:43], v[34:35], v[34:35]
	v_mov_b32_e32 v53, v44
	v_pk_mul_f32 v[54:55], v[46:47], v[46:47]
	v_mov_b32_e32 v52, v48
	v_mov_b32_e32 v44, v49
	v_mov_b32_e32 v50, v42
	v_mov_b32_e32 v51, v54
	v_mov_b32_e32 v54, v43
	v_pk_add_f32 v[42:43], v[52:53], v[44:45]
	v_pk_add_f32 v[44:45], v[50:51], v[54:55]
	v_and_b32_e32 v33, 0xffff0000, v33
	v_mov_b32_dpp v21, v43 quad_perm:[1,0,3,2] row_mask:0xf bank_mask:0xf
	v_mov_b32_dpp v20, v42 quad_perm:[1,0,3,2] row_mask:0xf bank_mask:0xf
	v_mov_b32_dpp v19, v45 quad_perm:[1,0,3,2] row_mask:0xf bank_mask:0xf
	v_mov_b32_dpp v18, v44 quad_perm:[1,0,3,2] row_mask:0xf bank_mask:0xf
	v_pk_add_f32 v[20:21], v[42:43], v[20:21]
	v_pk_add_f32 v[18:19], v[44:45], v[18:19]
	v_lshlrev_b32_e32 v30, 16, v31
	v_mov_b32_dpp v23, v21 quad_perm:[2,3,0,1] row_mask:0xf bank_mask:0xf
	v_mov_b32_dpp v22, v20 quad_perm:[2,3,0,1] row_mask:0xf bank_mask:0xf
	v_mov_b32_dpp v17, v19 quad_perm:[2,3,0,1] row_mask:0xf bank_mask:0xf
	v_mov_b32_dpp v16, v18 quad_perm:[2,3,0,1] row_mask:0xf bank_mask:0xf
	v_pk_add_f32 v[20:21], v[20:21], v[22:23]
	v_pk_add_f32 v[16:17], v[18:19], v[16:17]
	v_and_b32_e32 v31, 0xffff0000, v31
	v_mov_b32_dpp v25, v21 row_half_mirror row_mask:0xf bank_mask:0xf
	v_mov_b32_dpp v24, v20 row_half_mirror row_mask:0xf bank_mask:0xf
	v_mov_b32_dpp v15, v17 row_half_mirror row_mask:0xf bank_mask:0xf
	v_mov_b32_dpp v14, v16 row_half_mirror row_mask:0xf bank_mask:0xf
	v_pk_add_f32 v[18:19], v[20:21], v[24:25]
	v_pk_add_f32 v[14:15], v[16:17], v[14:15]
	v_lshlrev_b32_e32 v38, 16, v39
	v_mov_b32_dpp v27, v19 row_mirror row_mask:0xf bank_mask:0xf
	v_mov_b32_dpp v26, v18 row_mirror row_mask:0xf bank_mask:0xf
	v_mov_b32_dpp v13, v15 row_mirror row_mask:0xf bank_mask:0xf
	v_mov_b32_dpp v12, v14 row_mirror row_mask:0xf bank_mask:0xf
	v_pk_add_f32 v[16:17], v[18:19], v[26:27]
	v_pk_add_f32 v[12:13], v[14:15], v[12:13]
	ds_bpermute_b32 v15, v167, v17
	ds_bpermute_b32 v14, v167, v16
	ds_bpermute_b32 v19, v167, v13
	ds_bpermute_b32 v18, v167, v12
	v_and_b32_e32 v39, 0xffff0000, v39
	s_waitcnt lgkmcnt(2)
	v_pk_add_f32 v[14:15], v[16:17], v[14:15]
	ds_bpermute_b32 v17, v168, v15
	s_waitcnt lgkmcnt(1)
	v_pk_add_f32 v[12:13], v[12:13], v[18:19]
	ds_bpermute_b32 v16, v168, v14
	ds_bpermute_b32 v19, v168, v13
	ds_bpermute_b32 v18, v168, v12
	s_waitcnt lgkmcnt(2)
	v_pk_add_f32 v[14:15], v[14:15], v[16:17]
	s_nop 0
	v_pk_fma_f32 v[14:15], v[14:15], s[30:31], v[6:7] op_sel_hi:[1,0,0]
	s_waitcnt lgkmcnt(0)
	v_pk_add_f32 v[12:13], v[12:13], v[18:19]
	v_mul_f32_e32 v0, 0x4b800000, v15
	v_pk_fma_f32 v[6:7], v[12:13], s[30:31], v[6:7] op_sel_hi:[1,0,0]
	v_cmp_gt_f32_e64 s[8:9], s74, v15
	v_mul_f32_e32 v12, 0x4b800000, v14
	v_cmp_gt_f32_e32 vcc, s74, v14
	v_mul_f32_e32 v13, 0x4b800000, v7
	v_mul_f32_e32 v16, 0x4b800000, v6
	v_cmp_gt_f32_e64 s[4:5], s74, v6
	v_cmp_gt_f32_e64 s[6:7], s74, v7
	v_cndmask_b32_e64 v0, v15, v0, s[8:9]
	v_cndmask_b32_e32 v12, v14, v12, vcc
	v_cndmask_b32_e64 v7, v7, v13, s[6:7]
	v_cndmask_b32_e64 v6, v6, v16, s[4:5]
	v_rsq_f32_e32 v0, v0
	v_rsq_f32_e32 v12, v12
	v_rsq_f32_e32 v7, v7
	v_rsq_f32_e32 v13, v6
	v_mul_f32_e32 v6, 0x45800000, v0
	v_mul_f32_e32 v14, 0x45800000, v12
	v_mul_f32_e32 v15, 0x45800000, v7
	v_mul_f32_e32 v16, 0x45800000, v13
	v_cndmask_b32_e64 v0, v0, v6, s[8:9]
	v_cndmask_b32_e32 v6, v12, v14, vcc
	v_cndmask_b32_e64 v12, v7, v15, s[6:7]
	v_cndmask_b32_e64 v14, v13, v16, s[4:5]
	v_pk_mul_f32 v[16:17], v[0:1], v[36:37] op_sel_hi:[0,1]
	v_pk_mul_f32 v[6:7], v[6:7], v[40:41] op_sel_hi:[0,1]
	v_pk_mul_f32 v[12:13], v[12:13], v[46:47] op_sel_hi:[0,1]
	v_pk_mul_f32 v[14:15], v[14:15], v[34:35] op_sel_hi:[0,1]
	v_pk_mul_f32 v[16:17], v[16:17], v[32:33]
	v_pk_mul_f32 v[6:7], v[6:7], v[38:39]
	v_pk_mul_f32 v[12:13], v[12:13], v[28:29]
	v_pk_mul_f32 v[14:15], v[14:15], v[30:31]
	v_cvt_pk_bf16_f32 v0, v16, v17
	v_cvt_pk_bf16_f32 v6, v6, v7
	v_cvt_pk_bf16_f32 v7, v12, v13
	v_cvt_pk_bf16_f32 v12, v14, v15
	global_store_dword v[8:9], v0, off offset:512
	global_store_dword v[8:9], v6, off offset:768
	global_store_dword v[10:11], v7, off offset:1024
	global_store_dword v[8:9], v12, off offset:256
	s_cmp_eq_u32 s98, 0
	s_cbranch_scc1 .Lhgf_tail2
	s_ashr_i32 s4, s14, 2
	s_mov_b32 s6, 0x358637bd
	v_mov_b64_e32 v[6:7], s[6:7]
	s_ashr_i32 s5, s4, 31
	s_mul_i32 s6, s4, 0xc00
	s_mul_hi_i32 s7, s4, 0xc00
	s_add_u32 s6, s12, s6
	s_addc_u32 s7, s13, s7
	s_lshl_b64 s[4:5], s[4:5], 10
	v_lshl_add_u64 v[10:11], v[2:3], 2, s[6:7]
	v_lshl_add_u64 v[26:27], v[4:5], 0, s[4:5]
	v_lshl_add_u64 v[8:9], v[10:11], 0, s[20:21]
	global_load_dword v0, v[26:27], off
	global_load_dword v31, v[26:27], off offset:256
	v_add_co_u32_e32 v10, vcc, s81, v10
	global_load_dword v33, v[26:27], off offset:512
	global_load_dword v35, v[8:9], off offset:256
	global_load_dword v37, v[8:9], off offset:512
	v_addc_co_u32_e32 v11, vcc, 0, v11, vcc
	global_load_dword v39, v[26:27], off offset:768
	global_load_dword v41, v[8:9], off offset:768
	global_load_dword v47, v[10:11], off offset:1024
	s_add_i32 s14, s14, s41
	s_cmp_gt_i32 s14, 0xffff
	s_cselect_b32 s98, 0, 1
	v_mov_b32_e32 v85, v1
	v_mov_b32_e32 v84, v1
	v_mov_b32_e32 v83, v1
	v_mov_b32_e32 v82, v1
	v_mov_b32_e32 v87, v1
	v_mov_b32_e32 v86, v1
	v_mov_b32_e32 v81, v1
	v_mov_b32_e32 v80, v1
	v_mov_b32_e32 v89, v1
	v_mov_b32_e32 v88, v1
	v_mov_b32_e32 v79, v1
	v_mov_b32_e32 v78, v1
	v_mov_b32_e32 v91, v1
	v_mov_b32_e32 v90, v1
	v_mov_b32_e32 v77, v1
	v_mov_b32_e32 v76, v1
	s_waitcnt vmcnt(19)
	v_lshlrev_b32_e32 v92, 16, v64
	v_and_b32_e32 v93, 0xffff0000, v64
	s_waitcnt vmcnt(17)
	v_lshlrev_b32_e32 v96, 16, v97
	s_waitcnt vmcnt(16)
	v_lshlrev_b32_e32 v98, 16, v99
	s_waitcnt vmcnt(15)
	v_lshlrev_b32_e32 v100, 16, v101
	v_and_b32_e32 v101, 0xffff0000, v101
	s_waitcnt vmcnt(13)
	v_lshlrev_b32_e32 v104, 16, v105
	v_and_b32_e32 v105, 0xffff0000, v105
	v_and_b32_e32 v99, 0xffff0000, v99
	v_pk_mul_f32 v[108:109], v[100:101], v[100:101]
	s_waitcnt vmcnt(12)
	v_lshlrev_b32_e32 v110, 16, v111
	v_and_b32_e32 v111, 0xffff0000, v111
	v_pk_mul_f32 v[112:113], v[104:105], v[104:105]
	v_pk_mul_f32 v[106:107], v[98:99], v[98:99]
	v_mov_b32_e32 v117, v108
	v_pk_mul_f32 v[118:119], v[110:111], v[110:111]
	v_mov_b32_e32 v116, v112
	v_mov_b32_e32 v108, v113
	v_mov_b32_e32 v114, v106
	v_mov_b32_e32 v115, v118
	v_mov_b32_e32 v118, v107
	v_pk_add_f32 v[106:107], v[116:117], v[108:109]
	v_pk_add_f32 v[108:109], v[114:115], v[118:119]
	v_and_b32_e32 v97, 0xffff0000, v97
	v_mov_b32_dpp v85, v107 quad_perm:[1,0,3,2] row_mask:0xf bank_mask:0xf
	v_mov_b32_dpp v84, v106 quad_perm:[1,0,3,2] row_mask:0xf bank_mask:0xf
	v_mov_b32_dpp v83, v109 quad_perm:[1,0,3,2] row_mask:0xf bank_mask:0xf
	v_mov_b32_dpp v82, v108 quad_perm:[1,0,3,2] row_mask:0xf bank_mask:0xf
	v_pk_add_f32 v[84:85], v[106:107], v[84:85]
	v_pk_add_f32 v[82:83], v[108:109], v[82:83]
	v_lshlrev_b32_e32 v94, 16, v95
	v_mov_b32_dpp v87, v85 quad_perm:[2,3,0,1] row_mask:0xf bank_mask:0xf
	v_mov_b32_dpp v86, v84 quad_perm:[2,3,0,1] row_mask:0xf bank_mask:0xf
	v_mov_b32_dpp v81, v83 quad_perm:[2,3,0,1] row_mask:0xf bank_mask:0xf
	v_mov_b32_dpp v80, v82 quad_perm:[2,3,0,1] row_mask:0xf bank_mask:0xf
	v_pk_add_f32 v[84:85], v[84:85], v[86:87]
	v_pk_add_f32 v[80:81], v[82:83], v[80:81]
	v_and_b32_e32 v95, 0xffff0000, v95
	v_mov_b32_dpp v89, v85 row_half_mirror row_mask:0xf bank_mask:0xf
	v_mov_b32_dpp v88, v84 row_half_mirror row_mask:0xf bank_mask:0xf
	v_mov_b32_dpp v79, v81 row_half_mirror row_mask:0xf bank_mask:0xf
	v_mov_b32_dpp v78, v80 row_half_mirror row_mask:0xf bank_mask:0xf
	v_pk_add_f32 v[82:83], v[84:85], v[88:89]
	v_pk_add_f32 v[78:79], v[80:81], v[78:79]
	v_lshlrev_b32_e32 v102, 16, v103
	v_mov_b32_dpp v91, v83 row_mirror row_mask:0xf bank_mask:0xf
	v_mov_b32_dpp v90, v82 row_mirror row_mask:0xf bank_mask:0xf
	v_mov_b32_dpp v77, v79 row_mirror row_mask:0xf bank_mask:0xf
	v_mov_b32_dpp v76, v78 row_mirror row_mask:0xf bank_mask:0xf
	v_pk_add_f32 v[80:81], v[82:83], v[90:91]
	v_pk_add_f32 v[76:77], v[78:79], v[76:77]
	ds_bpermute_b32 v79, v167, v81
	ds_bpermute_b32 v78, v167, v80
	ds_bpermute_b32 v83, v167, v77
	ds_bpermute_b32 v82, v167, v76
	v_and_b32_e32 v103, 0xffff0000, v103
	s_waitcnt lgkmcnt(2)
	v_pk_add_f32 v[78:79], v[80:81], v[78:79]
	ds_bpermute_b32 v81, v168, v79
	s_waitcnt lgkmcnt(1)
	v_pk_add_f32 v[76:77], v[76:77], v[82:83]
	ds_bpermute_b32 v80, v168, v78
	ds_bpermute_b32 v83, v168, v77
	ds_bpermute_b32 v82, v168, v76
	s_waitcnt lgkmcnt(2)
	v_pk_add_f32 v[78:79], v[78:79], v[80:81]
	s_nop 0
	v_pk_fma_f32 v[78:79], v[78:79], s[30:31], v[70:71] op_sel_hi:[1,0,0]
	s_waitcnt lgkmcnt(0)
	v_pk_add_f32 v[76:77], v[76:77], v[82:83]
	v_mul_f32_e32 v64, 0x4b800000, v79
	v_pk_fma_f32 v[70:71], v[76:77], s[30:31], v[70:71] op_sel_hi:[1,0,0]
	v_cmp_gt_f32_e64 s[8:9], s74, v79
	v_mul_f32_e32 v76, 0x4b800000, v78
	v_cmp_gt_f32_e32 vcc, s74, v78
	v_mul_f32_e32 v77, 0x4b800000, v71
	v_mul_f32_e32 v80, 0x4b800000, v70
	v_cmp_gt_f32_e64 s[4:5], s74, v70
	v_cmp_gt_f32_e64 s[6:7], s74, v71
	v_cndmask_b32_e64 v64, v79, v64, s[8:9]
	v_cndmask_b32_e32 v76, v78, v76, vcc
	v_cndmask_b32_e64 v71, v71, v77, s[6:7]
	v_cndmask_b32_e64 v70, v70, v80, s[4:5]
	v_rsq_f32_e32 v64, v64
	v_rsq_f32_e32 v76, v76
	v_rsq_f32_e32 v71, v71
	v_rsq_f32_e32 v77, v70
	v_mul_f32_e32 v70, 0x45800000, v64
	v_mul_f32_e32 v78, 0x45800000, v76
	v_mul_f32_e32 v79, 0x45800000, v71
	v_mul_f32_e32 v80, 0x45800000, v77
	v_cndmask_b32_e64 v64, v64, v70, s[8:9]
	v_cndmask_b32_e32 v70, v76, v78, vcc
	v_cndmask_b32_e64 v76, v71, v79, s[6:7]
	v_cndmask_b32_e64 v78, v77, v80, s[4:5]
	v_pk_mul_f32 v[80:81], v[64:65], v[100:101] op_sel_hi:[0,1]
	v_pk_mul_f32 v[70:71], v[70:71], v[104:105] op_sel_hi:[0,1]
	v_pk_mul_f32 v[76:77], v[76:77], v[110:111] op_sel_hi:[0,1]
	v_pk_mul_f32 v[78:79], v[78:79], v[98:99] op_sel_hi:[0,1]
	v_pk_mul_f32 v[80:81], v[80:81], v[96:97]
	v_pk_mul_f32 v[70:71], v[70:71], v[102:103]
	v_pk_mul_f32 v[76:77], v[76:77], v[92:93]
	v_pk_mul_f32 v[78:79], v[78:79], v[94:95]
	v_cvt_pk_bf16_f32 v64, v80, v81
	v_cvt_pk_bf16_f32 v70, v70, v71
	v_cvt_pk_bf16_f32 v71, v76, v77
	v_cvt_pk_bf16_f32 v76, v78, v79
	global_store_dword v[72:73], v64, off offset:512
	global_store_dword v[72:73], v70, off offset:768
	global_store_dword v[74:75], v71, off offset:1024
	global_store_dword v[72:73], v76, off offset:256
	s_branch .Lhgf_loop
.Lhgf_tail1:
	s_waitcnt vmcnt(0)
	v_mov_b32_e32 v21, v1
	v_mov_b32_e32 v20, v1
	v_mov_b32_e32 v19, v1
	v_mov_b32_e32 v18, v1
	v_mov_b32_e32 v23, v1
	v_mov_b32_e32 v22, v1
	v_mov_b32_e32 v17, v1
	v_mov_b32_e32 v16, v1
	v_mov_b32_e32 v25, v1
	v_mov_b32_e32 v24, v1
	v_mov_b32_e32 v15, v1
	v_mov_b32_e32 v14, v1
	v_mov_b32_e32 v27, v1
	v_mov_b32_e32 v26, v1
	v_mov_b32_e32 v13, v1
	v_mov_b32_e32 v12, v1
	s_waitcnt vmcnt(7)
	v_lshlrev_b32_e32 v28, 16, v0
	v_and_b32_e32 v29, 0xffff0000, v0
	s_waitcnt vmcnt(5)
	v_lshlrev_b32_e32 v32, 16, v33
	s_waitcnt vmcnt(4)
	v_lshlrev_b32_e32 v34, 16, v35
	s_waitcnt vmcnt(3)
	v_lshlrev_b32_e32 v36, 16, v37
	v_and_b32_e32 v37, 0xffff0000, v37
	s_waitcnt vmcnt(1)
	v_lshlrev_b32_e32 v40, 16, v41
	v_and_b32_e32 v41, 0xffff0000, v41
	v_and_b32_e32 v35, 0xffff0000, v35
	v_pk_mul_f32 v[44:45], v[36:37], v[36:37]
	s_waitcnt vmcnt(0)
	v_lshlrev_b32_e32 v46, 16, v47
	v_and_b32_e32 v47, 0xffff0000, v47
	v_pk_mul_f32 v[48:49], v[40:41], v[40:41]
	v_pk_mul_f32 v[42:43], v[34:35], v[34:35]
	v_mov_b32_e32 v53, v44
	v_pk_mul_f32 v[54:55], v[46:47], v[46:47]
	v_mov_b32_e32 v52, v48
	v_mov_b32_e32 v44, v49
	v_mov_b32_e32 v50, v42
	v_mov_b32_e32 v51, v54
	v_mov_b32_e32 v54, v43
	v_pk_add_f32 v[42:43], v[52:53], v[44:45]
	v_pk_add_f32 v[44:45], v[50:51], v[54:55]
	v_and_b32_e32 v33, 0xffff0000, v33
	v_mov_b32_dpp v21, v43 quad_perm:[1,0,3,2] row_mask:0xf bank_mask:0xf
	v_mov_b32_dpp v20, v42 quad_perm:[1,0,3,2] row_mask:0xf bank_mask:0xf
	v_mov_b32_dpp v19, v45 quad_perm:[1,0,3,2] row_mask:0xf bank_mask:0xf
	v_mov_b32_dpp v18, v44 quad_perm:[1,0,3,2] row_mask:0xf bank_mask:0xf
	v_pk_add_f32 v[20:21], v[42:43], v[20:21]
	v_pk_add_f32 v[18:19], v[44:45], v[18:19]
	v_lshlrev_b32_e32 v30, 16, v31
	v_mov_b32_dpp v23, v21 quad_perm:[2,3,0,1] row_mask:0xf bank_mask:0xf
	v_mov_b32_dpp v22, v20 quad_perm:[2,3,0,1] row_mask:0xf bank_mask:0xf
	v_mov_b32_dpp v17, v19 quad_perm:[2,3,0,1] row_mask:0xf bank_mask:0xf
	v_mov_b32_dpp v16, v18 quad_perm:[2,3,0,1] row_mask:0xf bank_mask:0xf
	v_pk_add_f32 v[20:21], v[20:21], v[22:23]
	v_pk_add_f32 v[16:17], v[18:19], v[16:17]
	v_and_b32_e32 v31, 0xffff0000, v31
	v_mov_b32_dpp v25, v21 row_half_mirror row_mask:0xf bank_mask:0xf
	v_mov_b32_dpp v24, v20 row_half_mirror row_mask:0xf bank_mask:0xf
	v_mov_b32_dpp v15, v17 row_half_mirror row_mask:0xf bank_mask:0xf
	v_mov_b32_dpp v14, v16 row_half_mirror row_mask:0xf bank_mask:0xf
	v_pk_add_f32 v[18:19], v[20:21], v[24:25]
	v_pk_add_f32 v[14:15], v[16:17], v[14:15]
	v_lshlrev_b32_e32 v38, 16, v39
	v_mov_b32_dpp v27, v19 row_mirror row_mask:0xf bank_mask:0xf
	v_mov_b32_dpp v26, v18 row_mirror row_mask:0xf bank_mask:0xf
	v_mov_b32_dpp v13, v15 row_mirror row_mask:0xf bank_mask:0xf
	v_mov_b32_dpp v12, v14 row_mirror row_mask:0xf bank_mask:0xf
	v_pk_add_f32 v[16:17], v[18:19], v[26:27]
	v_pk_add_f32 v[12:13], v[14:15], v[12:13]
	ds_bpermute_b32 v15, v167, v17
	ds_bpermute_b32 v14, v167, v16
	ds_bpermute_b32 v19, v167, v13
	ds_bpermute_b32 v18, v167, v12
	v_and_b32_e32 v39, 0xffff0000, v39
	s_waitcnt lgkmcnt(2)
	v_pk_add_f32 v[14:15], v[16:17], v[14:15]
	ds_bpermute_b32 v17, v168, v15
	s_waitcnt lgkmcnt(1)
	v_pk_add_f32 v[12:13], v[12:13], v[18:19]
	ds_bpermute_b32 v16, v168, v14
	ds_bpermute_b32 v19, v168, v13
	ds_bpermute_b32 v18, v168, v12
	s_waitcnt lgkmcnt(2)
	v_pk_add_f32 v[14:15], v[14:15], v[16:17]
	s_nop 0
	v_pk_fma_f32 v[14:15], v[14:15], s[30:31], v[6:7] op_sel_hi:[1,0,0]
	s_waitcnt lgkmcnt(0)
	v_pk_add_f32 v[12:13], v[12:13], v[18:19]
	v_mul_f32_e32 v0, 0x4b800000, v15
	v_pk_fma_f32 v[6:7], v[12:13], s[30:31], v[6:7] op_sel_hi:[1,0,0]
	v_cmp_gt_f32_e64 s[8:9], s74, v15
	v_mul_f32_e32 v12, 0x4b800000, v14
	v_cmp_gt_f32_e32 vcc, s74, v14
	v_mul_f32_e32 v13, 0x4b800000, v7
	v_mul_f32_e32 v16, 0x4b800000, v6
	v_cmp_gt_f32_e64 s[4:5], s74, v6
	v_cmp_gt_f32_e64 s[6:7], s74, v7
	v_cndmask_b32_e64 v0, v15, v0, s[8:9]
	v_cndmask_b32_e32 v12, v14, v12, vcc
	v_cndmask_b32_e64 v7, v7, v13, s[6:7]
	v_cndmask_b32_e64 v6, v6, v16, s[4:5]
	v_rsq_f32_e32 v0, v0
	v_rsq_f32_e32 v12, v12
	v_rsq_f32_e32 v7, v7
	v_rsq_f32_e32 v13, v6
	v_mul_f32_e32 v6, 0x45800000, v0
	v_mul_f32_e32 v14, 0x45800000, v12
	v_mul_f32_e32 v15, 0x45800000, v7
	v_mul_f32_e32 v16, 0x45800000, v13
	v_cndmask_b32_e64 v0, v0, v6, s[8:9]
	v_cndmask_b32_e32 v6, v12, v14, vcc
	v_cndmask_b32_e64 v12, v7, v15, s[6:7]
	v_cndmask_b32_e64 v14, v13, v16, s[4:5]
	v_pk_mul_f32 v[16:17], v[0:1], v[36:37] op_sel_hi:[0,1]
	v_pk_mul_f32 v[6:7], v[6:7], v[40:41] op_sel_hi:[0,1]
	v_pk_mul_f32 v[12:13], v[12:13], v[46:47] op_sel_hi:[0,1]
	v_pk_mul_f32 v[14:15], v[14:15], v[34:35] op_sel_hi:[0,1]
	v_pk_mul_f32 v[16:17], v[16:17], v[32:33]
	v_pk_mul_f32 v[6:7], v[6:7], v[38:39]
	v_pk_mul_f32 v[12:13], v[12:13], v[28:29]
	v_pk_mul_f32 v[14:15], v[14:15], v[30:31]
	v_cvt_pk_bf16_f32 v0, v16, v17
	v_cvt_pk_bf16_f32 v6, v6, v7
	v_cvt_pk_bf16_f32 v7, v12, v13
	v_cvt_pk_bf16_f32 v12, v14, v15
	global_store_dword v[8:9], v0, off offset:512
	global_store_dword v[8:9], v6, off offset:768
	global_store_dword v[10:11], v7, off offset:1024
	global_store_dword v[8:9], v12, off offset:256
	s_branch .LBB0_170
.Lhgf_tail2:
	s_waitcnt vmcnt(0)
	v_mov_b32_e32 v85, v1
	v_mov_b32_e32 v84, v1
	v_mov_b32_e32 v83, v1
	v_mov_b32_e32 v82, v1
	v_mov_b32_e32 v87, v1
	v_mov_b32_e32 v86, v1
	v_mov_b32_e32 v81, v1
	v_mov_b32_e32 v80, v1
	v_mov_b32_e32 v89, v1
	v_mov_b32_e32 v88, v1
	v_mov_b32_e32 v79, v1
	v_mov_b32_e32 v78, v1
	v_mov_b32_e32 v91, v1
	v_mov_b32_e32 v90, v1
	v_mov_b32_e32 v77, v1
	v_mov_b32_e32 v76, v1
	s_waitcnt vmcnt(7)
	v_lshlrev_b32_e32 v92, 16, v64
	v_and_b32_e32 v93, 0xffff0000, v64
	s_waitcnt vmcnt(5)
	v_lshlrev_b32_e32 v96, 16, v97
	s_waitcnt vmcnt(4)
	v_lshlrev_b32_e32 v98, 16, v99
	s_waitcnt vmcnt(3)
	v_lshlrev_b32_e32 v100, 16, v101
	v_and_b32_e32 v101, 0xffff0000, v101
	s_waitcnt vmcnt(1)
	v_lshlrev_b32_e32 v104, 16, v105
	v_and_b32_e32 v105, 0xffff0000, v105
	v_and_b32_e32 v99, 0xffff0000, v99
	v_pk_mul_f32 v[108:109], v[100:101], v[100:101]
	s_waitcnt vmcnt(0)
	v_lshlrev_b32_e32 v110, 16, v111
	v_and_b32_e32 v111, 0xffff0000, v111
	v_pk_mul_f32 v[112:113], v[104:105], v[104:105]
	v_pk_mul_f32 v[106:107], v[98:99], v[98:99]
	v_mov_b32_e32 v117, v108
	v_pk_mul_f32 v[118:119], v[110:111], v[110:111]
	v_mov_b32_e32 v116, v112
	v_mov_b32_e32 v108, v113
	v_mov_b32_e32 v114, v106
	v_mov_b32_e32 v115, v118
	v_mov_b32_e32 v118, v107
	v_pk_add_f32 v[106:107], v[116:117], v[108:109]
	v_pk_add_f32 v[108:109], v[114:115], v[118:119]
	v_and_b32_e32 v97, 0xffff0000, v97
	v_mov_b32_dpp v85, v107 quad_perm:[1,0,3,2] row_mask:0xf bank_mask:0xf
	v_mov_b32_dpp v84, v106 quad_perm:[1,0,3,2] row_mask:0xf bank_mask:0xf
	v_mov_b32_dpp v83, v109 quad_perm:[1,0,3,2] row_mask:0xf bank_mask:0xf
	v_mov_b32_dpp v82, v108 quad_perm:[1,0,3,2] row_mask:0xf bank_mask:0xf
	v_pk_add_f32 v[84:85], v[106:107], v[84:85]
	v_pk_add_f32 v[82:83], v[108:109], v[82:83]
	v_lshlrev_b32_e32 v94, 16, v95
	v_mov_b32_dpp v87, v85 quad_perm:[2,3,0,1] row_mask:0xf bank_mask:0xf
	v_mov_b32_dpp v86, v84 quad_perm:[2,3,0,1] row_mask:0xf bank_mask:0xf
	v_mov_b32_dpp v81, v83 quad_perm:[2,3,0,1] row_mask:0xf bank_mask:0xf
	v_mov_b32_dpp v80, v82 quad_perm:[2,3,0,1] row_mask:0xf bank_mask:0xf
	v_pk_add_f32 v[84:85], v[84:85], v[86:87]
	v_pk_add_f32 v[80:81], v[82:83], v[80:81]
	v_and_b32_e32 v95, 0xffff0000, v95
	v_mov_b32_dpp v89, v85 row_half_mirror row_mask:0xf bank_mask:0xf
	v_mov_b32_dpp v88, v84 row_half_mirror row_mask:0xf bank_mask:0xf
	v_mov_b32_dpp v79, v81 row_half_mirror row_mask:0xf bank_mask:0xf
	v_mov_b32_dpp v78, v80 row_half_mirror row_mask:0xf bank_mask:0xf
	v_pk_add_f32 v[82:83], v[84:85], v[88:89]
	v_pk_add_f32 v[78:79], v[80:81], v[78:79]
	v_lshlrev_b32_e32 v102, 16, v103
	v_mov_b32_dpp v91, v83 row_mirror row_mask:0xf bank_mask:0xf
	v_mov_b32_dpp v90, v82 row_mirror row_mask:0xf bank_mask:0xf
	v_mov_b32_dpp v77, v79 row_mirror row_mask:0xf bank_mask:0xf
	v_mov_b32_dpp v76, v78 row_mirror row_mask:0xf bank_mask:0xf
	v_pk_add_f32 v[80:81], v[82:83], v[90:91]
	v_pk_add_f32 v[76:77], v[78:79], v[76:77]
	ds_bpermute_b32 v79, v167, v81
	ds_bpermute_b32 v78, v167, v80
	ds_bpermute_b32 v83, v167, v77
	ds_bpermute_b32 v82, v167, v76
	v_and_b32_e32 v103, 0xffff0000, v103
	s_waitcnt lgkmcnt(2)
	v_pk_add_f32 v[78:79], v[80:81], v[78:79]
	ds_bpermute_b32 v81, v168, v79
	s_waitcnt lgkmcnt(1)
	v_pk_add_f32 v[76:77], v[76:77], v[82:83]
	ds_bpermute_b32 v80, v168, v78
	ds_bpermute_b32 v83, v168, v77
	ds_bpermute_b32 v82, v168, v76
	s_waitcnt lgkmcnt(2)
	v_pk_add_f32 v[78:79], v[78:79], v[80:81]
	s_nop 0
	v_pk_fma_f32 v[78:79], v[78:79], s[30:31], v[70:71] op_sel_hi:[1,0,0]
	s_waitcnt lgkmcnt(0)
	v_pk_add_f32 v[76:77], v[76:77], v[82:83]
	v_mul_f32_e32 v64, 0x4b800000, v79
	v_pk_fma_f32 v[70:71], v[76:77], s[30:31], v[70:71] op_sel_hi:[1,0,0]
	v_cmp_gt_f32_e64 s[8:9], s74, v79
	v_mul_f32_e32 v76, 0x4b800000, v78
	v_cmp_gt_f32_e32 vcc, s74, v78
	v_mul_f32_e32 v77, 0x4b800000, v71
	v_mul_f32_e32 v80, 0x4b800000, v70
	v_cmp_gt_f32_e64 s[4:5], s74, v70
	v_cmp_gt_f32_e64 s[6:7], s74, v71
	v_cndmask_b32_e64 v64, v79, v64, s[8:9]
	v_cndmask_b32_e32 v76, v78, v76, vcc
	v_cndmask_b32_e64 v71, v71, v77, s[6:7]
	v_cndmask_b32_e64 v70, v70, v80, s[4:5]
	v_rsq_f32_e32 v64, v64
	v_rsq_f32_e32 v76, v76
	v_rsq_f32_e32 v71, v71
	v_rsq_f32_e32 v77, v70
	v_mul_f32_e32 v70, 0x45800000, v64
	v_mul_f32_e32 v78, 0x45800000, v76
	v_mul_f32_e32 v79, 0x45800000, v71
	v_mul_f32_e32 v80, 0x45800000, v77
	v_cndmask_b32_e64 v64, v64, v70, s[8:9]
	v_cndmask_b32_e32 v70, v76, v78, vcc
	v_cndmask_b32_e64 v76, v71, v79, s[6:7]
	v_cndmask_b32_e64 v78, v77, v80, s[4:5]
	v_pk_mul_f32 v[80:81], v[64:65], v[100:101] op_sel_hi:[0,1]
	v_pk_mul_f32 v[70:71], v[70:71], v[104:105] op_sel_hi:[0,1]
	v_pk_mul_f32 v[76:77], v[76:77], v[110:111] op_sel_hi:[0,1]
	v_pk_mul_f32 v[78:79], v[78:79], v[98:99] op_sel_hi:[0,1]
	v_pk_mul_f32 v[80:81], v[80:81], v[96:97]
	v_pk_mul_f32 v[70:71], v[70:71], v[102:103]
	v_pk_mul_f32 v[76:77], v[76:77], v[92:93]
	v_pk_mul_f32 v[78:79], v[78:79], v[94:95]
	v_cvt_pk_bf16_f32 v64, v80, v81
	v_cvt_pk_bf16_f32 v70, v70, v71
	v_cvt_pk_bf16_f32 v71, v76, v77
	v_cvt_pk_bf16_f32 v76, v78, v79
	global_store_dword v[72:73], v64, off offset:512
	global_store_dword v[72:73], v70, off offset:768
	global_store_dword v[74:75], v71, off offset:1024
	global_store_dword v[72:73], v76, off offset:256
